# same as previous (tail deferral + barrier rewrite + DPP sums + hoisted gains) with the barrier poll safety caps raised from 2^12 to 2^20 polls
# baseline (speedup 1.0000x reference)
; DI unsigned xb_ld(unsigned* p) { return __hip_atomic_load(p, __ATOMIC_RELAXED, __HIP_MEMORY_SCOPE_AGENT); }
; DI void xcd_barrier_complete(unsigned* bar, unsigned x, unsigned& nloc, unsigned& nx) {
;   const unsigned G = gridDim.x * gridDim.y * gridDim.z;
;   unsigned sum, cnt, mine, sp = 0u;
;   for (;;) {
;     sum = 0u; cnt = 0u; mine = 0u;
; #pragma unroll
;     for (unsigned j = 0; j < 16; ++j) { const unsigned c = xb_ld(&bar[XB_XCNT(j)]); sum += c; cnt += (c > 0u) ? 1u : 0u; mine = (j == x) ? c : mine; }
;     if (sum == G) break;
;     __builtin_amdgcn_s_sleep(1);
;     if ((++sp & 255u) == 0u) { if (xb_ld(&bar[XB_TMO])) break; if (sp > XB_SPIN_CAP) { atomicAdd(&bar[XB_TMO], 1u); break; } }
;   }
;   nloc = mine > 0u ? mine : 1u; nx = cnt > 0u ? cnt : 1u;
.Lfb_boot:
	global_load_dword v254, v253, s[98:99] sc1
	s_add_u32 s100, s100, 1
	s_waitcnt vmcnt(0)
	v_add_u32_dpp v255, v254, v254 quad_perm:[1,0,3,2] row_mask:0xf bank_mask:0xf
	s_nop 1
	v_add_u32_dpp v255, v255, v255 quad_perm:[2,3,0,1] row_mask:0xf bank_mask:0xf
	s_nop 1
	v_add_u32_dpp v255, v255, v255 row_half_mirror row_mask:0xf bank_mask:0xf
	s_nop 1
	v_add_u32_dpp v255, v255, v255 row_mirror row_mask:0xf bank_mask:0xf
	s_nop 1
	v_readfirstlane_b32 vcc_lo, v255
	s_cmp_eq_u32 vcc_lo, s101
	s_cbranch_scc1 .Lfb_bootdone
	s_cmp_lt_u32 s100, 0x100000
	s_cbranch_scc0 .Lfb_bootdone
	s_sleep 1
	s_branch .Lfb_boot

; DI unsigned xb_ld(unsigned* p) { return __hip_atomic_load(p, __ATOMIC_RELAXED, __HIP_MEMORY_SCOPE_AGENT); }
; DI unsigned xb_add(unsigned* p, unsigned v) { return __hip_atomic_fetch_add(p, v, __ATOMIC_RELAXED, __HIP_MEMORY_SCOPE_AGENT); }
; #define XB_SPIN(cond, bar) do { unsigned _sp = 0; while (cond) { __builtin_amdgcn_s_sleep(1); \
;     if ((++_sp & 255u) == 0u) { if (xb_ld(&(bar)[XB_TMO])) break; if (_sp > XB_SPIN_CAP) { atomicAdd(&(bar)[XB_TMO], 1u); break; } } } } while (0)
; DI void xcd_barrier(const XcdBarrier& b) {
;     ...
;       else XB_SPIN(xb_ld(&bar[XB_TOPGEN]) == tg, bar);
;       __builtin_amdgcn_fence(__ATOMIC_ACQUIRE, "agent");
;       xb_add(&bar[XB_XGEN(b.x)], 1u);
;       asm volatile("s_waitcnt vmcnt(0)" ::: "memory");
;     } else {
;       XB_SPIN(xb_ld(&bar[XB_XGEN(b.x)]) == gen, bar);
;       __builtin_amdgcn_fence(__ATOMIC_ACQUIRE, "agent");
;       asm volatile("s_waitcnt vmcnt(0)" ::: "memory");
.Lfb_loop_0:
	global_load_dword v254, v253, s[98:99] sc1
	s_add_u32 vcc_lo, vcc_lo, 1
	s_waitcnt vmcnt(0)
	v_readfirstlane_b32 vcc_hi, v254
	s_cmp_ge_u32 vcc_hi, s101
	s_cbranch_scc1 .Lfb_done_0
	s_cmp_lt_u32 vcc_lo, 0x100000
	s_cbranch_scc0 .Lfb_done_0
	s_sleep 1
	s_branch .Lfb_loop_0
